# v30 + lowrank GEMM epilogue: bias values loaded once per tile and reused (14 reload pairs and their store-draining waits removed)
# speedup vs baseline: 1.0264x; 1.0003x over previous
; DEV float sigm(float x) { return __builtin_amdgcn_rcpf(1.f + __expf(-x)); }
; DEV void phase_rw_lowrank(const Params& p, char* smem) {
;     ...
;               [&](int ru, int rl, int c, float v0, float v1) {
;                 bf16_t* o = out + (size_t)(r0 + ru) * 512 + c0;
;                 const unsigned off = (unsigned)(rl * 512 + c);
;                 const float z0 = bias[c0 + c] + v0, z1 = bias[c0 + c + 32] + v1;
;                 if (which < 2) { o[off] = f2bf(-0.6065306597f * sigm(z0)); o[off + 32] = f2bf(-0.6065306597f * sigm(z1)); }
;                 else { o[off] = f2bf(sigm(z0)); o[off + 32] = f2bf(sigm(z1)); }
.LBB0_1535:
	v_mov_b32_e32 v137, v131
	v_lshl_add_u64 v[96:97], s[70:71], 0, v[136:137]
	s_or_b32 s70, s68, 3
	s_ashr_i32 s71, s70, 31
	s_lshl_b64 s[70:71], s[70:71], 10
	s_add_u32 s70, s76, s70
	s_addc_u32 s71, s77, s71
	s_add_u32 s70, s70, s69
	s_addc_u32 s71, s71, 0
	v_cvt_pk_bf16_f32 v98, v112, s0
	global_store_short v138, v98, s[70:71]
	v_cvt_pk_bf16_f32 v98, v113, s0
	global_store_short v138, v98, s[70:71] offset:64
	global_load_dword v113, v[96:97], off offset:128
	global_load_dword v112, v[96:97], off
	s_and_b64 vcc, exec, s[8:9]
	s_mov_b64 s[70:71], -1
	s_waitcnt vmcnt(1)
	v_mov_b32_e32 v252, v113
	v_add_f32_e32 v98, v116, v113
	v_mul_f32_e32 v98, 0xbfb8aa3b, v98
	v_exp_f32_e32 v114, v98
	s_cbranch_vccnz .LBB0_1537
	v_add_f32_e32 v98, 1.0, v114
	v_rcp_f32_e32 v99, v98
	s_mov_b64 s[70:71], 0
.LBB0_1537:
	s_waitcnt vmcnt(0)
	v_mov_b32_e32 v253, v112
	v_add_f32_e32 v98, v100, v112
	v_mul_f32_e32 v98, 0xbfb8aa3b, v98
	v_exp_f32_e32 v98, v98
	s_andn2_b64 vcc, exec, s[70:71]
	v_add_f32_e32 v98, 1.0, v98
	v_rcp_f32_e32 v98, v98
	s_cbranch_vccnz .LBB0_1539
	v_add_f32_e32 v99, 1.0, v114
	v_rcp_f32_e32 v99, v99
	s_nop 0
	v_pk_mul_f32 v[98:99], v[98:99], s[66:67] op_sel_hi:[1,0]

; DEV float sigm(float x) { return __builtin_amdgcn_rcpf(1.f + __expf(-x)); }
; DEV void phase_rw_lowrank(const Params& p, char* smem) {
;     ...
;               [&](int ru, int rl, int c, float v0, float v1) {
;                 bf16_t* o = out + (size_t)(r0 + ru) * 512 + c0;
;                 const unsigned off = (unsigned)(rl * 512 + c);
;                 const float z0 = bias[c0 + c] + v0, z1 = bias[c0 + c + 32] + v1;
;                 if (which < 2) { o[off] = f2bf(-0.6065306597f * sigm(z0)); o[off + 32] = f2bf(-0.6065306597f * sigm(z1)); }
;                 else { o[off] = f2bf(sigm(z0)); o[off + 32] = f2bf(sigm(z1)); }
.LBB0_1551:
	s_or_b32 s70, s68, 11
	s_ashr_i32 s71, s70, 31
	s_lshl_b64 s[70:71], s[70:71], 10
	s_add_u32 s70, s76, s70
	s_addc_u32 s71, s77, s71
	s_add_u32 s70, s70, s69
	s_addc_u32 s71, s71, 0
	v_cvt_pk_bf16_f32 v98, v98, s0
	global_store_short v138, v98, s[70:71]
	v_cvt_pk_bf16_f32 v98, v99, s0
	global_store_short v138, v98, s[70:71] offset:64
	v_mov_b32_e32 v101, v252
	v_mov_b32_e32 v100, v253
	s_and_b64 vcc, exec, s[8:9]
	s_mov_b64 s[70:71], -1
	v_add_f32_e32 v98, v120, v101
	v_mul_f32_e32 v98, 0xbfb8aa3b, v98
	v_exp_f32_e32 v102, v98
	s_cbranch_vccnz .LBB0_1553
	v_add_f32_e32 v98, 1.0, v102
	v_rcp_f32_e32 v99, v98
	s_mov_b64 s[70:71], 0
.LBB0_1553:
	v_add_f32_e32 v98, v104, v100
	v_mul_f32_e32 v98, 0xbfb8aa3b, v98
	v_exp_f32_e32 v98, v98
	s_andn2_b64 vcc, exec, s[70:71]
	v_add_f32_e32 v98, 1.0, v98
	v_rcp_f32_e32 v98, v98
	s_cbranch_vccnz .LBB0_1555
	v_add_f32_e32 v99, 1.0, v102
	v_rcp_f32_e32 v99, v99
	s_nop 0
	v_pk_mul_f32 v[98:99], v[98:99], s[66:67] op_sel_hi:[1,0]

; DEV float sigm(float x) { return __builtin_amdgcn_rcpf(1.f + __expf(-x)); }
; DEV void phase_rw_lowrank(const Params& p, char* smem) {
;     ...
;                 bf16_t* o = out + (size_t)(r0 + ru) * 512 + c0;
;                 const unsigned off = (unsigned)(rl * 512 + c);
;                 const float z0 = bias[c0 + c] + v0, z1 = bias[c0 + c + 32] + v1;
;                 if (which < 2) { o[off] = f2bf(-0.6065306597f * sigm(z0)); o[off + 32] = f2bf(-0.6065306597f * sigm(z1)); }
;                 else { o[off] = f2bf(sigm(z0)); o[off + 32] = f2bf(sigm(z1)); }
.LBB0_1567:
	s_or_b32 s70, s68, 19
	s_ashr_i32 s71, s70, 31
	s_lshl_b64 s[70:71], s[70:71], 10
	s_add_u32 s70, s76, s70
	s_addc_u32 s71, s77, s71
	s_add_u32 s70, s70, s69
	s_addc_u32 s71, s71, 0
	v_cvt_pk_bf16_f32 v98, v98, s0
	global_store_short v138, v98, s[70:71]
	v_cvt_pk_bf16_f32 v98, v99, s0
	global_store_short v138, v98, s[70:71] offset:64
	v_mov_b32_e32 v101, v252
	v_mov_b32_e32 v100, v253
	s_and_b64 vcc, exec, s[8:9]
	s_mov_b64 s[70:71], -1
	v_add_f32_e32 v98, v124, v101
	v_mul_f32_e32 v98, 0xbfb8aa3b, v98
	v_exp_f32_e32 v102, v98
	s_cbranch_vccnz .LBB0_1569
	v_add_f32_e32 v98, 1.0, v102
	v_rcp_f32_e32 v99, v98
	s_mov_b64 s[70:71], 0
.LBB0_1569:
	v_add_f32_e32 v98, v108, v100
	v_mul_f32_e32 v98, 0xbfb8aa3b, v98
	v_exp_f32_e32 v98, v98
	s_andn2_b64 vcc, exec, s[70:71]
	v_add_f32_e32 v98, 1.0, v98
	v_rcp_f32_e32 v98, v98
	s_cbranch_vccnz .LBB0_1571
	v_add_f32_e32 v99, 1.0, v102
	v_rcp_f32_e32 v99, v99
	s_nop 0
	v_pk_mul_f32 v[98:99], v[98:99], s[66:67] op_sel_hi:[1,0]

; DEV float sigm(float x) { return __builtin_amdgcn_rcpf(1.f + __expf(-x)); }
; DEV void phase_rw_lowrank(const Params& p, char* smem) {
;     ...
;                 bf16_t* o = out + (size_t)(r0 + ru) * 512 + c0;
;                 const unsigned off = (unsigned)(rl * 512 + c);
;                 const float z0 = bias[c0 + c] + v0, z1 = bias[c0 + c + 32] + v1;
;                 if (which < 2) { o[off] = f2bf(-0.6065306597f * sigm(z0)); o[off + 32] = f2bf(-0.6065306597f * sigm(z1)); }
;                 else { o[off] = f2bf(sigm(z0)); o[off + 32] = f2bf(sigm(z1)); }
.LBB0_1583:
	s_or_b32 s70, s68, 27
	s_ashr_i32 s71, s70, 31
	s_lshl_b64 s[70:71], s[70:71], 10
	s_add_u32 s70, s76, s70
	s_addc_u32 s71, s77, s71
	s_add_u32 s70, s70, s69
	s_addc_u32 s71, s71, 0
	v_cvt_pk_bf16_f32 v98, v98, s0
	global_store_short v138, v98, s[70:71]
	v_cvt_pk_bf16_f32 v98, v99, s0
	global_store_short v138, v98, s[70:71] offset:64
	v_mov_b32_e32 v101, v252
	v_mov_b32_e32 v100, v253
	s_and_b64 vcc, exec, s[8:9]
	s_mov_b64 s[70:71], -1
	v_add_f32_e32 v80, v80, v101
	v_mul_f32_e32 v80, 0xbfb8aa3b, v80
	v_exp_f32_e32 v80, v80
	s_cbranch_vccnz .LBB0_1585
	v_add_f32_e32 v98, 1.0, v80
	v_rcp_f32_e32 v99, v98
	s_mov_b64 s[70:71], 0
.LBB0_1585:
	v_add_f32_e32 v64, v64, v100
	v_mul_f32_e32 v64, 0xbfb8aa3b, v64
	v_exp_f32_e32 v64, v64
	s_andn2_b64 vcc, exec, s[70:71]
	v_add_f32_e32 v64, 1.0, v64
	v_rcp_f32_e32 v98, v64
	s_cbranch_vccnz .LBB0_1587
	v_add_f32_e32 v64, 1.0, v80
	v_rcp_f32_e32 v99, v64
	s_nop 0
	v_pk_mul_f32 v[98:99], v[98:99], s[66:67] op_sel_hi:[1,0]

; DEV float sigm(float x) { return __builtin_amdgcn_rcpf(1.f + __expf(-x)); }
; DEV void phase_rw_lowrank(const Params& p, char* smem) {
;     ...
;                 bf16_t* o = out + (size_t)(r0 + ru) * 512 + c0;
;                 const unsigned off = (unsigned)(rl * 512 + c);
;                 const float z0 = bias[c0 + c] + v0, z1 = bias[c0 + c + 32] + v1;
;                 if (which < 2) { o[off] = f2bf(-0.6065306597f * sigm(z0)); o[off + 32] = f2bf(-0.6065306597f * sigm(z1)); }
;                 else { o[off] = f2bf(sigm(z0)); o[off + 32] = f2bf(sigm(z1)); }
.LBB0_1599:
	s_or_b32 s70, s68, 35
	s_ashr_i32 s71, s70, 31
	s_lshl_b64 s[70:71], s[70:71], 10
	s_add_u32 s70, s76, s70
	s_addc_u32 s71, s77, s71
	s_add_u32 s70, s70, s69
	s_addc_u32 s71, s71, 0
	v_cvt_pk_bf16_f32 v64, v64, s0
	global_store_short v138, v64, s[70:71]
	v_cvt_pk_bf16_f32 v64, v65, s0
	global_store_short v138, v64, s[70:71] offset:64
	v_mov_b32_e32 v67, v252
	v_mov_b32_e32 v66, v253
	s_and_b64 vcc, exec, s[8:9]
	s_mov_b64 s[70:71], -1
	v_add_f32_e32 v64, v84, v67
	v_mul_f32_e32 v64, 0xbfb8aa3b, v64
	v_exp_f32_e32 v80, v64
	s_cbranch_vccnz .LBB0_1601
	v_add_f32_e32 v64, 1.0, v80
	v_rcp_f32_e32 v65, v64
	s_mov_b64 s[70:71], 0
.LBB0_1601:
	v_add_f32_e32 v64, v68, v66
	v_mul_f32_e32 v64, 0xbfb8aa3b, v64
	v_exp_f32_e32 v64, v64
	s_andn2_b64 vcc, exec, s[70:71]
	v_add_f32_e32 v64, 1.0, v64
	v_rcp_f32_e32 v64, v64
	s_cbranch_vccnz .LBB0_1603
	v_add_f32_e32 v65, 1.0, v80
	v_rcp_f32_e32 v65, v65
	s_nop 0
	v_pk_mul_f32 v[64:65], v[64:65], s[66:67] op_sel_hi:[1,0]

; DEV float sigm(float x) { return __builtin_amdgcn_rcpf(1.f + __expf(-x)); }
; DEV void phase_rw_lowrank(const Params& p, char* smem) {
;     ...
;                 bf16_t* o = out + (size_t)(r0 + ru) * 512 + c0;
;                 const unsigned off = (unsigned)(rl * 512 + c);
;                 const float z0 = bias[c0 + c] + v0, z1 = bias[c0 + c + 32] + v1;
;                 if (which < 2) { o[off] = f2bf(-0.6065306597f * sigm(z0)); o[off + 32] = f2bf(-0.6065306597f * sigm(z1)); }
;                 else { o[off] = f2bf(sigm(z0)); o[off + 32] = f2bf(sigm(z1)); }
.LBB0_1615:
	s_or_b32 s70, s68, 43
	s_ashr_i32 s71, s70, 31
	s_lshl_b64 s[70:71], s[70:71], 10
	s_add_u32 s70, s76, s70
	s_addc_u32 s71, s77, s71
	s_add_u32 s70, s70, s69
	s_addc_u32 s71, s71, 0
	v_cvt_pk_bf16_f32 v64, v64, s0
	global_store_short v138, v64, s[70:71]
	v_cvt_pk_bf16_f32 v64, v65, s0
	global_store_short v138, v64, s[70:71] offset:64
	v_mov_b32_e32 v67, v252
	v_mov_b32_e32 v66, v253
	s_and_b64 vcc, exec, s[8:9]
	s_mov_b64 s[70:71], -1
	v_add_f32_e32 v64, v88, v67
	v_mul_f32_e32 v64, 0xbfb8aa3b, v64
	v_exp_f32_e32 v68, v64
	s_cbranch_vccnz .LBB0_1617
	v_add_f32_e32 v64, 1.0, v68
	v_rcp_f32_e32 v65, v64
	s_mov_b64 s[70:71], 0
.LBB0_1617:
	v_add_f32_e32 v64, v72, v66
	v_mul_f32_e32 v64, 0xbfb8aa3b, v64
	v_exp_f32_e32 v64, v64
	s_andn2_b64 vcc, exec, s[70:71]
	v_add_f32_e32 v64, 1.0, v64
	v_rcp_f32_e32 v64, v64
	s_cbranch_vccnz .LBB0_1619
	v_add_f32_e32 v65, 1.0, v68
	v_rcp_f32_e32 v65, v65
	s_nop 0
	v_pk_mul_f32 v[64:65], v[64:65], s[66:67] op_sel_hi:[1,0]

; DEV float sigm(float x) { return __builtin_amdgcn_rcpf(1.f + __expf(-x)); }
; DEV void phase_rw_lowrank(const Params& p, char* smem) {
;     ...
;                 bf16_t* o = out + (size_t)(r0 + ru) * 512 + c0;
;                 const unsigned off = (unsigned)(rl * 512 + c);
;                 const float z0 = bias[c0 + c] + v0, z1 = bias[c0 + c + 32] + v1;
;                 if (which < 2) { o[off] = f2bf(-0.6065306597f * sigm(z0)); o[off + 32] = f2bf(-0.6065306597f * sigm(z1)); }
;                 else { o[off] = f2bf(sigm(z0)); o[off + 32] = f2bf(sigm(z1)); }
.LBB0_1631:
	s_or_b32 s70, s68, 51
	s_ashr_i32 s71, s70, 31
	s_lshl_b64 s[70:71], s[70:71], 10
	s_add_u32 s70, s76, s70
	s_addc_u32 s71, s77, s71
	s_add_u32 s70, s70, s69
	s_addc_u32 s71, s71, 0
	v_cvt_pk_bf16_f32 v64, v64, s0
	global_store_short v138, v64, s[70:71]
	v_cvt_pk_bf16_f32 v64, v65, s0
	global_store_short v138, v64, s[70:71] offset:64
	v_mov_b32_e32 v67, v252
	v_mov_b32_e32 v66, v253
	s_and_b64 vcc, exec, s[8:9]
	s_mov_b64 s[70:71], -1
	v_add_f32_e32 v64, v92, v67
	v_mul_f32_e32 v64, 0xbfb8aa3b, v64
	v_exp_f32_e32 v68, v64
	s_cbranch_vccnz .LBB0_1633
	v_add_f32_e32 v64, 1.0, v68
	v_rcp_f32_e32 v65, v64
	s_mov_b64 s[70:71], 0
.LBB0_1633:
	v_add_f32_e32 v64, v76, v66
	v_mul_f32_e32 v64, 0xbfb8aa3b, v64
	v_exp_f32_e32 v64, v64
	s_andn2_b64 vcc, exec, s[70:71]
	v_add_f32_e32 v64, 1.0, v64
	v_rcp_f32_e32 v64, v64
	s_cbranch_vccnz .LBB0_1635
	v_add_f32_e32 v65, 1.0, v68
	v_rcp_f32_e32 v65, v65
	s_nop 0
	v_pk_mul_f32 v[64:65], v[64:65], s[66:67] op_sel_hi:[1,0]

; DEV float sigm(float x) { return __builtin_amdgcn_rcpf(1.f + __expf(-x)); }
; DEV void phase_rw_lowrank(const Params& p, char* smem) {
;     ...
;                 bf16_t* o = out + (size_t)(r0 + ru) * 512 + c0;
;                 const unsigned off = (unsigned)(rl * 512 + c);
;                 const float z0 = bias[c0 + c] + v0, z1 = bias[c0 + c + 32] + v1;
;                 if (which < 2) { o[off] = f2bf(-0.6065306597f * sigm(z0)); o[off + 32] = f2bf(-0.6065306597f * sigm(z1)); }
;                 else { o[off] = f2bf(sigm(z0)); o[off + 32] = f2bf(sigm(z1)); }
.LBB0_1647:
	s_or_b32 s70, s68, 59
	s_ashr_i32 s71, s70, 31
	s_lshl_b64 s[70:71], s[70:71], 10
	s_add_u32 s70, s76, s70
	s_addc_u32 s71, s77, s71
	s_add_u32 s70, s70, s69
	s_addc_u32 s71, s71, 0
	v_cvt_pk_bf16_f32 v64, v64, s0
	global_store_short v138, v64, s[70:71]
	v_cvt_pk_bf16_f32 v64, v65, s0
	global_store_short v138, v64, s[70:71] offset:64
	v_mov_b32_e32 v67, v252
	v_mov_b32_e32 v66, v253
	s_and_b64 vcc, exec, s[8:9]
	s_mov_b64 s[70:71], -1
	v_add_f32_e32 v48, v48, v67
	v_mul_f32_e32 v48, 0xbfb8aa3b, v48
	v_exp_f32_e32 v48, v48
	s_cbranch_vccnz .LBB0_1649
	v_add_f32_e32 v64, 1.0, v48
	v_rcp_f32_e32 v65, v64
	s_mov_b64 s[70:71], 0
.LBB0_1649:
	v_add_f32_e32 v32, v32, v66
	v_mul_f32_e32 v32, 0xbfb8aa3b, v32
	v_exp_f32_e32 v32, v32
	s_andn2_b64 vcc, exec, s[70:71]
	v_add_f32_e32 v32, 1.0, v32
	v_rcp_f32_e32 v64, v32
	s_cbranch_vccnz .LBB0_1651
	v_add_f32_e32 v32, 1.0, v48
	v_rcp_f32_e32 v65, v32
	s_nop 0
	v_pk_mul_f32 v[64:65], v[64:65], s[66:67] op_sel_hi:[1,0]

; DEV float sigm(float x) { return __builtin_amdgcn_rcpf(1.f + __expf(-x)); }
; DEV void phase_rw_lowrank(const Params& p, char* smem) {
;     ...
;                 bf16_t* o = out + (size_t)(r0 + ru) * 512 + c0;
;                 const unsigned off = (unsigned)(rl * 512 + c);
;                 const float z0 = bias[c0 + c] + v0, z1 = bias[c0 + c + 32] + v1;
;                 if (which < 2) { o[off] = f2bf(-0.6065306597f * sigm(z0)); o[off + 32] = f2bf(-0.6065306597f * sigm(z1)); }
;                 else { o[off] = f2bf(sigm(z0)); o[off + 32] = f2bf(sigm(z1)); }
.LBB0_1663:
	s_or_b32 s70, s68, 0x43
	s_ashr_i32 s71, s70, 31
	s_lshl_b64 s[70:71], s[70:71], 10
	s_add_u32 s70, s76, s70
	s_addc_u32 s71, s77, s71
	s_add_u32 s70, s70, s69
	s_addc_u32 s71, s71, 0
	v_cvt_pk_bf16_f32 v32, v32, s0
	global_store_short v138, v32, s[70:71]
	v_cvt_pk_bf16_f32 v32, v33, s0
	global_store_short v138, v32, s[70:71] offset:64
	v_mov_b32_e32 v35, v252
	v_mov_b32_e32 v34, v253
	s_and_b64 vcc, exec, s[8:9]
	s_mov_b64 s[70:71], -1
	v_add_f32_e32 v32, v52, v35
	v_mul_f32_e32 v32, 0xbfb8aa3b, v32
	v_exp_f32_e32 v48, v32
	s_cbranch_vccnz .LBB0_1665
	v_add_f32_e32 v32, 1.0, v48
	v_rcp_f32_e32 v33, v32
	s_mov_b64 s[70:71], 0
.LBB0_1665:
	v_add_f32_e32 v32, v36, v34
	v_mul_f32_e32 v32, 0xbfb8aa3b, v32
	v_exp_f32_e32 v32, v32
	s_andn2_b64 vcc, exec, s[70:71]
	v_add_f32_e32 v32, 1.0, v32
	v_rcp_f32_e32 v32, v32
	s_cbranch_vccnz .LBB0_1667
	v_add_f32_e32 v33, 1.0, v48
	v_rcp_f32_e32 v33, v33
	s_nop 0
	v_pk_mul_f32 v[32:33], v[32:33], s[66:67] op_sel_hi:[1,0]

; DEV float sigm(float x) { return __builtin_amdgcn_rcpf(1.f + __expf(-x)); }
; DEV void phase_rw_lowrank(const Params& p, char* smem) {
;     ...
;                 bf16_t* o = out + (size_t)(r0 + ru) * 512 + c0;
;                 const unsigned off = (unsigned)(rl * 512 + c);
;                 const float z0 = bias[c0 + c] + v0, z1 = bias[c0 + c + 32] + v1;
;                 if (which < 2) { o[off] = f2bf(-0.6065306597f * sigm(z0)); o[off + 32] = f2bf(-0.6065306597f * sigm(z1)); }
;                 else { o[off] = f2bf(sigm(z0)); o[off + 32] = f2bf(sigm(z1)); }
.LBB0_1679:
	s_or_b32 s70, s68, 0x4b
	s_ashr_i32 s71, s70, 31
	s_lshl_b64 s[70:71], s[70:71], 10
	s_add_u32 s70, s76, s70
	s_addc_u32 s71, s77, s71
	s_add_u32 s70, s70, s69
	s_addc_u32 s71, s71, 0
	v_cvt_pk_bf16_f32 v32, v32, s0
	global_store_short v138, v32, s[70:71]
	v_cvt_pk_bf16_f32 v32, v33, s0
	global_store_short v138, v32, s[70:71] offset:64
	v_mov_b32_e32 v35, v252
	v_mov_b32_e32 v34, v253
	s_and_b64 vcc, exec, s[8:9]
	s_mov_b64 s[70:71], -1
	v_add_f32_e32 v32, v56, v35
	v_mul_f32_e32 v32, 0xbfb8aa3b, v32
	v_exp_f32_e32 v36, v32
	s_cbranch_vccnz .LBB0_1681
	v_add_f32_e32 v32, 1.0, v36
	v_rcp_f32_e32 v33, v32
	s_mov_b64 s[70:71], 0
.LBB0_1681:
	v_add_f32_e32 v32, v40, v34
	v_mul_f32_e32 v32, 0xbfb8aa3b, v32
	v_exp_f32_e32 v32, v32
	s_andn2_b64 vcc, exec, s[70:71]
	v_add_f32_e32 v32, 1.0, v32
	v_rcp_f32_e32 v32, v32
	s_cbranch_vccnz .LBB0_1683
	v_add_f32_e32 v33, 1.0, v36
	v_rcp_f32_e32 v33, v33
	s_nop 0
	v_pk_mul_f32 v[32:33], v[32:33], s[66:67] op_sel_hi:[1,0]

; DEV float sigm(float x) { return __builtin_amdgcn_rcpf(1.f + __expf(-x)); }
; DEV void phase_rw_lowrank(const Params& p, char* smem) {
;     ...
;                 bf16_t* o = out + (size_t)(r0 + ru) * 512 + c0;
;                 const unsigned off = (unsigned)(rl * 512 + c);
;                 const float z0 = bias[c0 + c] + v0, z1 = bias[c0 + c + 32] + v1;
;                 if (which < 2) { o[off] = f2bf(-0.6065306597f * sigm(z0)); o[off + 32] = f2bf(-0.6065306597f * sigm(z1)); }
;                 else { o[off] = f2bf(sigm(z0)); o[off + 32] = f2bf(sigm(z1)); }
.LBB0_1695:
	s_or_b32 s70, s68, 0x53
	s_ashr_i32 s71, s70, 31
	s_lshl_b64 s[70:71], s[70:71], 10
	s_add_u32 s70, s76, s70
	s_addc_u32 s71, s77, s71
	s_add_u32 s70, s70, s69
	s_addc_u32 s71, s71, 0
	v_cvt_pk_bf16_f32 v32, v32, s0
	global_store_short v138, v32, s[70:71]
	v_cvt_pk_bf16_f32 v32, v33, s0
	global_store_short v138, v32, s[70:71] offset:64
	v_mov_b32_e32 v35, v252
	v_mov_b32_e32 v34, v253
	s_and_b64 vcc, exec, s[8:9]
	s_mov_b64 s[70:71], -1
	v_add_f32_e32 v32, v60, v35
	v_mul_f32_e32 v32, 0xbfb8aa3b, v32
	v_exp_f32_e32 v36, v32
	s_cbranch_vccnz .LBB0_1697
	v_add_f32_e32 v32, 1.0, v36
	v_rcp_f32_e32 v33, v32
	s_mov_b64 s[70:71], 0
.LBB0_1697:
	v_add_f32_e32 v32, v44, v34
	v_mul_f32_e32 v32, 0xbfb8aa3b, v32
	v_exp_f32_e32 v32, v32
	s_andn2_b64 vcc, exec, s[70:71]
	v_add_f32_e32 v32, 1.0, v32
	v_rcp_f32_e32 v32, v32
	s_cbranch_vccnz .LBB0_1699
	v_add_f32_e32 v33, 1.0, v36
	v_rcp_f32_e32 v33, v33
	s_nop 0
	v_pk_mul_f32 v[32:33], v[32:33], s[66:67] op_sel_hi:[1,0]

; DEV float sigm(float x) { return __builtin_amdgcn_rcpf(1.f + __expf(-x)); }
; DEV void phase_rw_lowrank(const Params& p, char* smem) {
;     ...
;                 bf16_t* o = out + (size_t)(r0 + ru) * 512 + c0;
;                 const unsigned off = (unsigned)(rl * 512 + c);
;                 const float z0 = bias[c0 + c] + v0, z1 = bias[c0 + c + 32] + v1;
;                 if (which < 2) { o[off] = f2bf(-0.6065306597f * sigm(z0)); o[off + 32] = f2bf(-0.6065306597f * sigm(z1)); }
;                 else { o[off] = f2bf(sigm(z0)); o[off + 32] = f2bf(sigm(z1)); }
.LBB0_1711:
	s_or_b32 s70, s68, 0x5b
	s_ashr_i32 s71, s70, 31
	s_lshl_b64 s[70:71], s[70:71], 10
	s_add_u32 s70, s76, s70
	s_addc_u32 s71, s77, s71
	s_add_u32 s70, s70, s69
	s_addc_u32 s71, s71, 0
	v_cvt_pk_bf16_f32 v32, v32, s0
	global_store_short v138, v32, s[70:71]
	v_cvt_pk_bf16_f32 v32, v33, s0
	global_store_short v138, v32, s[70:71] offset:64
	v_mov_b32_e32 v35, v252
	v_mov_b32_e32 v34, v253
	s_and_b64 vcc, exec, s[8:9]
	s_mov_b64 s[70:71], -1
	v_add_f32_e32 v16, v16, v35
	v_mul_f32_e32 v16, 0xbfb8aa3b, v16
	v_exp_f32_e32 v16, v16
	s_cbranch_vccnz .LBB0_1713
	v_add_f32_e32 v32, 1.0, v16
	v_rcp_f32_e32 v33, v32
	s_mov_b64 s[70:71], 0
.LBB0_1713:
	v_add_f32_e32 v0, v0, v34
	v_mul_f32_e32 v0, 0xbfb8aa3b, v0
	v_exp_f32_e32 v0, v0
	s_andn2_b64 vcc, exec, s[70:71]
	v_add_f32_e32 v0, 1.0, v0
	v_rcp_f32_e32 v32, v0
	s_cbranch_vccnz .LBB0_1715
	v_add_f32_e32 v0, 1.0, v16
	v_rcp_f32_e32 v33, v0
	s_nop 0
	v_pk_mul_f32 v[32:33], v[32:33], s[66:67] op_sel_hi:[1,0]

; DEV float sigm(float x) { return __builtin_amdgcn_rcpf(1.f + __expf(-x)); }
; DEV void phase_rw_lowrank(const Params& p, char* smem) {
;     ...
;                 bf16_t* o = out + (size_t)(r0 + ru) * 512 + c0;
;                 const unsigned off = (unsigned)(rl * 512 + c);
;                 const float z0 = bias[c0 + c] + v0, z1 = bias[c0 + c + 32] + v1;
;                 if (which < 2) { o[off] = f2bf(-0.6065306597f * sigm(z0)); o[off + 32] = f2bf(-0.6065306597f * sigm(z1)); }
;                 else { o[off] = f2bf(sigm(z0)); o[off + 32] = f2bf(sigm(z1)); }
.LBB0_1727:
	s_or_b32 s70, s68, 0x63
	s_ashr_i32 s71, s70, 31
	s_lshl_b64 s[70:71], s[70:71], 10
	s_add_u32 s70, s76, s70
	s_addc_u32 s71, s77, s71
	s_add_u32 s70, s70, s69
	s_addc_u32 s71, s71, 0
	v_cvt_pk_bf16_f32 v0, v0, s0
	global_store_short v138, v0, s[70:71]
	v_cvt_pk_bf16_f32 v0, v1, s0
	global_store_short v138, v0, s[70:71] offset:64
	v_mov_b32_e32 v3, v252
	v_mov_b32_e32 v2, v253
	s_and_b64 vcc, exec, s[8:9]
	s_mov_b64 s[70:71], -1
	v_add_f32_e32 v0, v20, v3
	v_mul_f32_e32 v0, 0xbfb8aa3b, v0
	v_exp_f32_e32 v16, v0
	s_cbranch_vccnz .LBB0_1729
	v_add_f32_e32 v0, 1.0, v16
	v_rcp_f32_e32 v1, v0
	s_mov_b64 s[70:71], 0
.LBB0_1729:
	v_add_f32_e32 v0, v4, v2
	v_mul_f32_e32 v0, 0xbfb8aa3b, v0
	v_exp_f32_e32 v0, v0
	s_andn2_b64 vcc, exec, s[70:71]
	v_add_f32_e32 v0, 1.0, v0
	v_rcp_f32_e32 v0, v0
	s_cbranch_vccnz .LBB0_1731
	v_add_f32_e32 v1, 1.0, v16
	v_rcp_f32_e32 v1, v1
	s_nop 0
	v_pk_mul_f32 v[0:1], v[0:1], s[66:67] op_sel_hi:[1,0]

; DEV float sigm(float x) { return __builtin_amdgcn_rcpf(1.f + __expf(-x)); }
; DEV void phase_rw_lowrank(const Params& p, char* smem) {
;     ...
;                 bf16_t* o = out + (size_t)(r0 + ru) * 512 + c0;
;                 const unsigned off = (unsigned)(rl * 512 + c);
;                 const float z0 = bias[c0 + c] + v0, z1 = bias[c0 + c + 32] + v1;
;                 if (which < 2) { o[off] = f2bf(-0.6065306597f * sigm(z0)); o[off + 32] = f2bf(-0.6065306597f * sigm(z1)); }
;                 else { o[off] = f2bf(sigm(z0)); o[off + 32] = f2bf(sigm(z1)); }
.LBB0_1743:
	s_or_b32 s70, s68, 0x6b
	s_ashr_i32 s71, s70, 31
	s_lshl_b64 s[70:71], s[70:71], 10
	s_add_u32 s70, s76, s70
	s_addc_u32 s71, s77, s71
	s_add_u32 s70, s70, s69
	s_addc_u32 s71, s71, 0
	v_cvt_pk_bf16_f32 v0, v0, s0
	global_store_short v138, v0, s[70:71]
	v_cvt_pk_bf16_f32 v0, v1, s0
	global_store_short v138, v0, s[70:71] offset:64
	v_mov_b32_e32 v3, v252
	v_mov_b32_e32 v2, v253
	s_and_b64 vcc, exec, s[8:9]
	s_mov_b64 s[70:71], -1
	v_add_f32_e32 v0, v24, v3
	v_mul_f32_e32 v0, 0xbfb8aa3b, v0
	v_exp_f32_e32 v4, v0
	s_cbranch_vccnz .LBB0_1745
	v_add_f32_e32 v0, 1.0, v4
	v_rcp_f32_e32 v1, v0
	s_mov_b64 s[70:71], 0
.LBB0_1745:
	v_add_f32_e32 v0, v8, v2
	v_mul_f32_e32 v0, 0xbfb8aa3b, v0
	v_exp_f32_e32 v0, v0
	s_andn2_b64 vcc, exec, s[70:71]
	v_add_f32_e32 v0, 1.0, v0
	v_rcp_f32_e32 v0, v0
	s_cbranch_vccnz .LBB0_1747
	v_add_f32_e32 v1, 1.0, v4
	v_rcp_f32_e32 v1, v1
	s_nop 0
	v_pk_mul_f32 v[0:1], v[0:1], s[66:67] op_sel_hi:[1,0]

; DEV float sigm(float x) { return __builtin_amdgcn_rcpf(1.f + __expf(-x)); }
; DEV void phase_rw_lowrank(const Params& p, char* smem) {
;     ...
;                 bf16_t* o = out + (size_t)(r0 + ru) * 512 + c0;
;                 const unsigned off = (unsigned)(rl * 512 + c);
;                 const float z0 = bias[c0 + c] + v0, z1 = bias[c0 + c + 32] + v1;
;                 if (which < 2) { o[off] = f2bf(-0.6065306597f * sigm(z0)); o[off + 32] = f2bf(-0.6065306597f * sigm(z1)); }
;                 else { o[off] = f2bf(sigm(z0)); o[off + 32] = f2bf(sigm(z1)); }
.LBB0_1759:
	s_or_b32 s70, s68, 0x73
	s_ashr_i32 s71, s70, 31
	s_lshl_b64 s[70:71], s[70:71], 10
	s_add_u32 s70, s76, s70
	s_addc_u32 s71, s77, s71
	s_add_u32 s70, s70, s69
	s_addc_u32 s71, s71, 0
	v_cvt_pk_bf16_f32 v0, v0, s0
	global_store_short v138, v0, s[70:71]
	v_cvt_pk_bf16_f32 v0, v1, s0
	global_store_short v138, v0, s[70:71] offset:64
	v_mov_b32_e32 v3, v252
	v_mov_b32_e32 v2, v253
	s_and_b64 vcc, exec, s[8:9]
	s_mov_b64 s[70:71], -1
	v_add_f32_e32 v0, v28, v3
	v_mul_f32_e32 v0, 0xbfb8aa3b, v0
	v_exp_f32_e32 v4, v0
	s_cbranch_vccnz .LBB0_1761
	v_add_f32_e32 v0, 1.0, v4
	v_rcp_f32_e32 v1, v0
	s_mov_b64 s[70:71], 0
.LBB0_1761:
	v_add_f32_e32 v0, v12, v2
	v_mul_f32_e32 v0, 0xbfb8aa3b, v0
	v_exp_f32_e32 v0, v0
	s_andn2_b64 vcc, exec, s[70:71]
	v_add_f32_e32 v0, 1.0, v0
	v_rcp_f32_e32 v0, v0
	s_cbranch_vccnz .LBB0_1763
	v_add_f32_e32 v1, 1.0, v4
	v_rcp_f32_e32 v1, v1
	s_nop 0
	v_pk_mul_f32 v[0:1], v[0:1], s[66:67] op_sel_hi:[1,0]
